# G6 start skew (8 groups x ~1us) to spread the epilogue store bursts; on top of v75
# speedup vs baseline: 1.0050x; 1.0050x over previous
_Z6mk_fwdILi0EEv4Args:
	s_load_dword s89, s[0:1], 0xc8
	s_add_u32 s4, s0, 0xc8
	s_addc_u32 s5, s1, 0
	v_readfirstlane_b32 s33, v0
	v_writelane_b32 v255, s4, 0
	s_waitcnt lgkmcnt(0)
	s_and_b32 s3, s89, 7
	s_cmp_eq_u32 s3, 0
	v_writelane_b32 v255, s5, 1
	s_mov_b32 s79, s2
	s_mov_b32 s100, s2
	s_cselect_b64 s[80:81], -1, 0
	s_cmp_lg_u32 s3, 0
	s_mov_b32 s78, s2
	s_cbranch_scc1 .LBB0_2
	s_ashr_i32 s4, s2, 31
	s_lshr_b32 s4, s4, 29
	s_add_i32 s4, s2, s4
	s_ashr_i32 s5, s4, 3
	s_and_b32 s4, s4, -8
	s_ashr_i32 s3, s89, 3
	s_sub_i32 s4, s2, s4
	s_mul_i32 s3, s3, s4
	s_add_i32 s78, s3, s5

.LBB0_1377:
	s_cmp_lt_i32 s16, 1
	s_cbranch_scc1 .LBB0_1393
	s_bfe_u32 s0, s100, 0x30003
	s_cmp_eq_u32 s0, 0
	s_cbranch_scc1 .Lskew_done_g6
.Lskew_loop_g6:
	s_sleep 32
	s_sub_u32 s0, s0, 1
	s_cmp_lg_u32 s0, 0
	s_cbranch_scc1 .Lskew_loop_g6
.Lskew_done_g6:
	s_lshl_b32 s17, s88, 10
	v_lshl_add_u32 v0, v26, 4, s17
	v_add_u32_e32 v1, 0x2000, v0
	v_ashrrev_i32_e32 v2, 31, v1
	v_lshrrev_b32_e32 v2, 22, v2
	v_add_u32_e32 v2, v1, v2
	v_ashrrev_i32_e32 v8, 10, v2
	v_mul_i32_i24_e32 v2, 0x400, v8
	v_sub_u32_e32 v1, v1, v2
	v_lshrrev_b32_e32 v2, 4, v1
	v_bitop3_b32 v1, v2, v1, 32 bitop3:0x6c
	v_ashrrev_i32_e32 v2, 31, v1
	v_lshrrev_b32_e32 v2, 26, v2
	v_add_u32_e32 v2, v1, v2
	v_ashrrev_i32_e32 v9, 6, v2
	v_lshlrev_b32_e32 v3, 3, v8
	v_and_b32_e32 v2, 0xffc0, v2
	v_and_b32_e32 v3, -16, v3
	v_sub_u32_e32 v1, v1, v2
	v_add_u32_e32 v3, v9, v3
	v_lshrrev_b16_e32 v2, 7, v1
	v_and_b32_e32 v4, 3, v9
	s_mov_b32 s2, 0xffffe0
	v_lshrrev_b32_e32 v5, 2, v3
	v_lshlrev_b32_e32 v6, 1, v3
	v_and_b32_e32 v2, 1, v2
	v_and_or_b32 v4, v3, s2, v4
	v_and_b32_e32 v5, 4, v5
	v_and_b32_e32 v6, 24, v6
	v_add_u16_e32 v1, v1, v2
	v_mov_b32_e32 v2, 1
	v_or3_b32 v4, v4, v5, v6
	v_lshlrev_b32_e32 v5, 5, v8
	v_ashrrev_i16_sdwa v1, v2, sext(v1) dst_sel:DWORD dst_unused:UNUSED_PAD src0_sel:DWORD src1_sel:BYTE_0
	s_movk_i32 s0, 0xb00
	v_and_b32_e32 v10, 32, v5
	v_bfe_i32 v11, v1, 0, 16
	v_mul_u32_u24_e32 v4, 0xb00, v4
	v_add_u32_e32 v1, v10, v11
	v_mul_lo_u32 v3, v3, s0
	v_add_lshl_u32 v160, v4, v1, 1
	v_add_lshl_u32 v162, v1, v3, 1
	v_ashrrev_i32_e32 v1, 31, v0
	v_lshrrev_b32_e32 v1, 22, v1
	v_add_u32_e32 v1, v0, v1
	v_ashrrev_i32_e32 v12, 10, v1
	v_mul_i32_i24_e32 v1, 0x400, v12
	v_sub_u32_e32 v0, v0, v1
	v_lshrrev_b32_e32 v1, 4, v0
	v_bitop3_b32 v0, v1, v0, 32 bitop3:0x6c
	v_ashrrev_i32_e32 v1, 31, v0
	v_lshrrev_b32_e32 v1, 26, v1
	v_add_u32_e32 v1, v0, v1
	v_lshlrev_b32_e32 v3, 3, v12
	s_lshr_b32 s1, s33, 8
	v_ashrrev_i32_e32 v13, 6, v1
	v_and_b32_e32 v3, -16, v3
	v_and_b32_e32 v1, 0xc0, v1
	s_add_u32 s20, s40, 0x2100000
	v_add_u32_e32 v3, v13, v3
	v_and_b32_e32 v4, 3, v13
	v_sub_u32_e32 v0, v0, v1
	s_addc_u32 s21, s41, 0
	v_and_or_b32 v4, v3, s2, v4
	v_ashrrev_i16_sdwa v0, v2, sext(v0) dst_sel:DWORD dst_unused:UNUSED_PAD src0_sel:DWORD src1_sel:BYTE_0
	s_add_i32 s2, 0, 0x20200
	v_bfe_i32 v15, v0, 0, 16
	v_mov_b32_e32 v0, s2
	ds_read_b96 v[0:2], v0
	v_lshrrev_b32_e32 v5, 2, v3
	v_lshlrev_b32_e32 v6, 1, v3
	v_and_b32_e32 v5, 4, v5
	v_and_b32_e32 v6, 24, v6
	s_waitcnt lgkmcnt(0)
	v_readfirstlane_b32 s2, v2
	v_readfirstlane_b32 s38, v1
	s_cmp_eq_u32 s2, 0
	v_or3_b32 v4, v4, v5, v6
	v_lshlrev_b32_e32 v5, 5, v12
	s_cselect_b32 s3, s20, 0
	s_mul_i32 s9, s38, 0x160000
	v_and_b32_e32 v14, 32, v5
	s_cselect_b32 s2, s21, 0
	s_mul_hi_i32 s8, s38, 0x160000
	s_cselect_b32 s12, s19, 0
	s_cselect_b32 s13, s18, 0
	s_add_u32 s10, s3, s9
	v_mul_u32_u24_e32 v4, 0xb00, v4
	v_add_u32_e32 v5, v14, v15
	s_addc_u32 s11, s2, s8
	s_add_i32 s22, s17, 0
	v_add_lshl_u32 v164, v4, v5, 1
	s_add_i32 m0, s22, 0x10000
	v_readfirstlane_b32 s39, v0
	global_load_lds_dwordx4 v164, s[10:11]
	s_add_i32 m0, s22, 0x12000
	s_add_u32 s2, s10, 0xb0000
	global_load_lds_dwordx4 v160, s[10:11]
	s_addc_u32 s3, s11, 0
	s_add_i32 m0, s22, 0x14000
	s_mul_i32 s7, s39, 0x160000
	global_load_lds_dwordx4 v164, s[2:3]
	s_add_i32 m0, s22, 0x16000
	s_mul_hi_i32 s6, s39, 0x160000
	s_add_u32 s8, s13, s7
	v_mul_lo_u32 v3, v3, s0
	s_addc_u32 s9, s12, s6
	s_add_i32 s23, s22, 0x2000
	v_add_lshl_u32 v166, v5, v3, 1
	global_load_lds_dwordx4 v160, s[2:3]
	s_mov_b32 m0, s22
	s_add_u32 s2, s8, 0xb0000
	global_load_lds_dwordx4 v166, s[8:9]
	s_mov_b32 m0, s23
	s_addc_u32 s3, s9, 0
	s_add_i32 s24, s22, 0x4000
	global_load_lds_dwordx4 v162, s[8:9]
	s_mov_b32 m0, s24
	s_add_i32 s25, s22, 0x6000
	global_load_lds_dwordx4 v166, s[2:3]
	s_mov_b32 m0, s25
	v_mov_b32_e32 v165, 0
	global_load_lds_dwordx4 v162, s[2:3]
	v_mov_b32_e32 v161, v165
	v_mov_b32_e32 v167, v165
	v_mov_b32_e32 v163, v165
	s_mov_b32 s26, 0
	v_lshl_add_u64 v[6:7], s[10:11], 0, v[164:165]
	v_lshl_add_u64 v[4:5], s[10:11], 0, v[160:161]
	v_lshl_add_u64 v[2:3], s[8:9], 0, v[166:167]
	s_cmp_lg_u32 s1, 1
	v_lshl_add_u64 v[0:1], s[8:9], 0, v[162:163]
	s_cbranch_scc1 .LBB0_1380
	s_barrier
